# strategy 4 on the S5 pass-2 phase: waves 0-3 (two scan tasks each) run at static s_setprio 2 so the wave pair of a SIMD finishes together (on v52)
# speedup vs baseline: 1.0193x; 1.0029x over previous
.Ls5_gen0:
	v_readlane_b32 s4, v253, 8
	s_cmp_lt_u32 s4, 4
	s_cbranch_scc0 .Ls5_prio_skip
	s_setprio 2
.Ls5_prio_skip:
	s_add_i32 s4, s6, s4
	s_cmpk_gt_i32 s4, 0xbff
	s_cbranch_scc1 .LBB0_188
	v_ashrrev_i32_e32 v4, 5, v168
	v_lshlrev_b32_e32 v108, 3, v4
	v_readlane_b32 s8, v253, 4
	v_and_b32_e32 v167, 31, v168
	v_ashrrev_i32_e32 v109, 31, v108
	v_readlane_b32 s9, v253, 5
	v_lshlrev_b32_e32 v160, 5, v167
	v_and_b32_e32 v169, 15, v168
	s_waitcnt lgkmcnt(0)
	v_lshl_add_u64 v[0:1], v[108:109], 1, s[8:9]
	v_readlane_b32 s8, v253, 2
	v_ashrrev_i32_e32 v5, 4, v168
	v_lshl_add_u64 v[110:111], v[0:1], 0, v[160:161]
	v_lshlrev_b32_e32 v160, 8, v169
	v_readlane_b32 s9, v253, 3
	v_lshlrev_b32_e32 v2, 3, v5
	v_ashrrev_i32_e32 v3, 31, v2
	v_lshl_add_u64 v[0:1], s[8:9], 0, v[160:161]
	s_mul_i32 s8, s18, 0x300
	s_ashr_i32 s9, s8, 31
	s_mov_b32 s10, s18
	s_mov_b32 s7, s27
	v_readlane_b32 s12, v252, 3
	v_lshl_add_u64 v[112:113], v[2:3], 1, v[0:1]
	s_lshl_b64 s[8:9], s[8:9], 2
	v_readlane_b32 s22, v252, 13
	v_xor_b32_e32 v0, 32, v220
	v_readlane_b32 s23, v252, 14
	v_readlane_b32 s27, v252, 18
	s_add_u32 s8, s22, s8
	v_lshlrev_b32_e32 v114, 2, v5
	v_cmp_lt_i32_e32 vcc, v0, v221
	s_mov_b32 s27, s7
	s_addc_u32 s9, s23, s9
	v_ashrrev_i32_e32 v115, 31, v114
	v_cndmask_b32_e32 v0, v220, v0, vcc
	v_lshlrev_b32_e32 v160, 2, v167
	v_readlane_b32 s7, v253, 10
	v_and_b32_e32 v1, -16, v168
	v_lshl_add_u64 v[116:117], v[114:115], 2, s[8:9]
	v_lshlrev_b32_e32 v234, 2, v0
	v_add_u32_e32 v0, s7, v160
	v_add_u32_e32 v1, s7, v1
	v_readlane_b32 s8, v252, 40
	s_movk_i32 s7, 0x440
	v_readlane_b32 s9, v252, 41
	v_mul_lo_u32 v2, v4, s7
	v_readlane_b32 s7, v253, 8
	v_readlane_b32 s20, v252, 11
	v_readlane_b32 s21, v252, 12
	v_lshl_add_u64 v[118:119], v[114:115], 1, s[8:9]
	s_add_i32 s8, s6, s7
	v_readlane_b32 s6, v254, 39
	v_readlane_b32 s18, v252, 9
	v_readlane_b32 s20, v255, 17
	v_mul_u32_u24_e32 v3, 0x110, v169
	v_readlane_b32 s7, v254, 40
	s_mov_b32 s18, s10
	v_readlane_b32 s21, v255, 18
	v_cmp_gt_u32_e64 s[36:37], 32, v168
	v_lshl_add_u64 v[120:121], s[6:7], 0, v[160:161]
	v_add_u32_e32 v235, v0, v2
	v_add_u32_e32 v236, v1, v3
	v_readlane_b32 s13, v252, 4
	v_readlane_b32 s14, v252, 5
	v_readlane_b32 s15, v252, 6
	v_readlane_b32 s16, v252, 7
	v_readlane_b32 s17, v252, 8
	v_readlane_b32 s19, v252, 10
	v_readlane_b32 s24, v252, 15
	v_readlane_b32 s25, v252, 16
	v_readlane_b32 s26, v252, 17

.LBB0_188:
	s_setprio 0
	s_branch .LBB0_145
